# sample-scan unit folded into the helper waves of scan_prompt (overlaps the prompt recurrence); hipcc scan_sample path removed
# baseline (speedup 1.0000x reference)
.LBB0_508:
	v_readlane_b32 s0, v254, 28
	v_readlane_b32 s1, v254, 29
	s_add_i32 s8, s8, s90
	s_xor_b64 s[42:43], s[42:43], s[0:1]
	s_branch .LBB0_613
.LBB0_509:
	v_mov_b32_e32 v57, v241
	s_ashr_i32 s48, s8, 5
	s_bfe_u32 s9, s8, 0x40001
	v_readfirstlane_b32 s0, v57
	s_and_b32 s10, s8, 1
	s_ashr_i32 s11, s0, 6
	s_ashr_i32 s49, s48, 31
	s_cmp_gt_i32 s11, 3
	s_mov_b64 s[0:1], -1
	s_cbranch_scc0 .LBB0_606
	s_waitcnt vmcnt(0)
	v_add_u32_e32 v198, 0xffffff00, v241
	v_lshrrev_b32_e32 v206, 3, v198
	v_and_b32_e32 v207, 7, v198
	s_lshl_b32 s0, s9, 6
	v_lshl_add_u32 v208, v207, 2, s0
	v_cmp_eq_u32_e64 s[38:39], 0, v207
	v_cmp_gt_u32_e64 s[28:29], 16, v206
	s_cmp_eq_u32 s10, 0
	s_cselect_b64 s[40:41], -1, 0
	s_nop 3
	s_and_b64 s[40:41], s[40:41], s[38:39]
	v_lshlrev_b32_e32 v199, 2, v208
	v_readlane_b32 s4, v255, 32
	v_readlane_b32 s5, v255, 33
	v_readlane_b32 s12, v255, 47
	v_readlane_b32 s13, v255, 48
	v_readlane_b32 s0, v255, 49
	v_readlane_b32 s1, v255, 50
	s_nop 4
	s_add_u32 s6, s4, 0x1000
	s_addc_u32 s7, s5, 0
	global_load_dwordx4 v[0:3], v199, s[4:5]
	global_load_dwordx4 v[4:7], v199, s[4:5] offset:128
	global_load_dwordx4 v[8:11], v199, s[6:7]
	global_load_dwordx4 v[12:15], v199, s[6:7] offset:128
	s_add_u32 s6, s4, 0x2000
	s_addc_u32 s7, s5, 0
	global_load_dwordx4 v[24:27], v199, s[12:13]
	global_load_dwordx4 v[28:31], v199, s[12:13] offset:128
	global_load_dwordx4 v[16:19], v199, s[6:7]
	global_load_dwordx4 v[20:23], v199, s[6:7] offset:128
	global_load_dwordx4 v[32:35], v199, s[0:1]
	global_load_dwordx4 v[36:39], v199, s[0:1] offset:128
	global_load_dwordx4 v[40:43], v199, s[64:65]
	global_load_dwordx4 v[44:47], v199, s[64:65] offset:128
	s_lshr_b32 s55, s8, 1
	s_cmp_lt_u32 s11, 6
	s_cbranch_scc0 .Lhs_p1l_skip
	v_add_u32_e32 v174, 0xffffff00, v241
	v_lshrrev_b32_e32 v172, 4, v174
	v_and_b32_e32 v174, 15, v174
	s_lshl_b32 s50, s10, 3
	v_add_u32_e32 v171, s50, v172
	v_lshlrev_b32_e32 v171, 6, v171
	v_lshl_add_u32 v171, v174, 2, v171
	v_lshlrev_b32_e32 v170, 2, v171
	v_lshlrev_b32_e32 v171, 1, v171
	global_load_dwordx4 v[96:99], v170, s[4:5]
	global_load_dwordx4 v[104:107], v170, s[6:7]
	global_load_dwordx4 v[108:111], v170, s[12:13]
	global_load_dwordx4 v[112:115], v170, s[0:1]
	global_load_dwordx4 v[116:119], v170, s[64:65]
	s_add_u32 s50, s4, 0x1000
	s_addc_u32 s51, s5, 0
	global_load_dwordx4 v[100:103], v170, s[50:51]
	v_readlane_b32 s52, v254, 41
	v_readlane_b32 s53, v254, 42
	v_readlane_b32 s54, v255, 43
	s_nop 4
	s_add_i32 s54, s54, s55
	s_mul_i32 s54, s54, 0x3400
	s_add_u32 s52, s52, s54
	s_addc_u32 s53, s53, 0
	s_add_u32 s56, s52, 0x1000
	s_addc_u32 s57, s53, 0
	s_add_u32 s58, s52, 0x2000
	s_addc_u32 s59, s53, 0
	global_load_dwordx4 v[84:87], v170, s[52:53]
	global_load_dwordx4 v[88:91], v170, s[56:57]
	global_load_dwordx4 v[92:95], v170, s[58:59]
	s_add_i32 s60, s55, 0x4080
	s_mul_i32 s61, s60, 0x1a00
	s_add_u32 s62, s86, 0x81a8000
	s_addc_u32 s63, s87, 0
	s_add_u32 s62, s62, s61
	s_addc_u32 s63, s63, 0
	s_add_u32 s50, s62, 0x1000
	s_addc_u32 s51, s63, 0
	global_load_dwordx2 v[120:121], v171, s[62:63]
	global_load_dwordx2 v[122:123], v171, s[62:63] offset:2048
	global_load_dwordx2 v[124:125], v171, s[50:51]
	s_lshl_b32 s61, s60, 11
	s_add_u32 s56, s86, 0xeb48000
	s_addc_u32 s57, s87, 0
	s_add_u32 s56, s56, s61
	s_addc_u32 s57, s57, 0
	s_add_u32 s58, s86, 0x10bc8000
	s_addc_u32 s59, s87, 0
	s_add_u32 s58, s58, s61
	s_addc_u32 s59, s59, 0
	global_load_dwordx2 v[126:127], v171, s[56:57]
	global_load_dwordx2 v[128:129], v171, s[58:59]
.Lhs_p1l_skip:
	v_mov_b32_e32 v48, 0x3fb8aa3b
	v_mov_b32_e32 v49, 0x3fb8aa3b
	s_mul_i32 s0, s48, 0x810
	v_add_u32_e32 v209, s0, v206
	v_mov_b32_e32 v211, 0
	v_lshlrev_b32_e32 v210, 1, v208
	s_movk_i32 s14, 0x1a00
	v_mad_u64_u32 v[182:183], s[0:1], v209, s14, v[210:211]
	s_add_u32 s4, s86, 0x81a7000
	s_addc_u32 s5, s87, 0
	v_lshl_add_u64 v[182:183], v[182:183], 0, s[4:5]
	s_mov_b64 s[0:1], 0x1000
	v_lshl_add_u64 v[178:179], v[182:183], 0, s[0:1]
	v_lshl_add_u64 v[180:181], v[178:179], 0, s[0:1]
	v_lshl_add_u32 v198, v209, 11, v210
	v_mov_b32_e32 v210, v198
	s_add_u32 s4, s86, 0xeb48000
	s_addc_u32 s5, s87, 0
	v_lshl_add_u64 v[186:187], v[210:211], 0, s[4:5]
	s_add_u32 s4, s86, 0x10bc8000
	s_addc_u32 s5, s87, 0
	v_lshl_add_u64 v[188:189], v[210:211], 0, s[4:5]
	s_lshl_b32 s0, s9, 6
	s_lshl_b32 s1, s10, 5
	s_add_i32 s0, s0, s1
	v_lshl_add_u32 v198, v207, 2, s0
	v_lshlrev_b32_e32 v198, 1, v198
	v_lshl_add_u32 v210, v209, 11, v198
	s_add_u32 s4, s86, 0x5700000
	s_addc_u32 s5, s87, 0
	v_lshl_add_u64 v[190:191], v[210:211], 0, s[4:5]
	s_lshl_b32 s0, s9, 2
	v_lshl_add_u32 v210, v209, 6, s0
	s_add_u32 s4, s86, 0x7884000
	s_addc_u32 s5, s87, 0
	v_lshl_add_u64 v[192:193], v[210:211], 0, s[4:5]
	v_mul_u32_u24_e32 v194, 0x600, v206
	v_lshl_add_u32 v194, v207, 4, v194
	s_lshl_b32 s0, s10, 7
	v_mul_u32_u24_e32 v222, 0x600, v206
	v_lshl_add_u32 v222, v207, 4, v222
	v_add_u32_e32 v222, s0, v222
	v_lshlrev_b32_e32 v195, 7, v206
	v_lshl_add_u32 v195, v207, 4, v195
	v_add_u32_e32 v195, 0x18000, v195
	v_lshlrev_b32_e32 v196, 2, v206
	v_add_u32_e32 v196, 0x1a000, v196
	v_lshlrev_b32_e32 v197, 3, v206
	v_add_u32_e32 v197, 0x1a100, v197
	s_lshl_b32 s50, s55, 4
	s_add_i32 s50, s50, s46
	s_lshl_b32 s51, s10, 3
	s_add_i32 s50, s50, s51
	s_lshl_b32 s50, s50, 14
	v_lshlrev_b32_e32 v210, 8, v206
	v_lshl_add_u32 v210, v207, 4, v210
	v_add_u32_e32 v210, s50, v210
	v_readlane_b32 s52, v254, 39
	v_readlane_b32 s53, v254, 40
	v_readlane_b32 s56, v255, 26
	v_readlane_b32 s57, v255, 27
	s_nop 4
	v_lshl_add_u64 v[250:251], v[210:211], 0, s[52:53]
	v_lshl_add_u64 v[236:237], v[210:211], 0, s[56:57]
	v_lshlrev_b32_e32 v238, 4, v207
	v_add_u32_e32 v238, 0x1d000, v238
	v_lshlrev_b32_e32 v239, 2, v206
	v_add_u32_e32 v240, 0x1a400, v239
	v_add_u32_e32 v239, 0x1d500, v239
	global_load_dwordx2 v[52:53], v[178:179], off
	global_load_dwordx2 v[54:55], v[178:179], off offset:64
	global_load_dwordx2 v[56:57], v[178:179], off offset:2048
	global_load_dwordx2 v[58:59], v[178:179], off offset:2112
	global_load_dwordx2 v[60:61], v[180:181], off
	global_load_dwordx2 v[62:63], v[180:181], off offset:64
	global_load_dwordx2 v[64:65], v[182:183], off offset:-2560
	global_load_dwordx2 v[66:67], v[182:183], off offset:-2496
	global_load_dwordx2 v[68:69], v[182:183], off offset:-512
	global_load_dwordx2 v[70:71], v[182:183], off offset:-448
	global_load_dwordx2 v[72:73], v[178:179], off offset:-2560
	global_load_dwordx2 v[74:75], v[178:179], off offset:-2496
	global_load_dwordx2 v[76:77], v[186:187], off
	global_load_dwordx2 v[78:79], v[186:187], off offset:64
	global_load_dwordx2 v[80:81], v[188:189], off
	global_load_dwordx2 v[82:83], v[188:189], off offset:64
	s_mov_b32 s13, 0
	s_waitcnt vmcnt(0)
	s_cmp_lt_u32 s11, 6
	s_cbranch_scc0 .Lhs_p1c_skip
	v_lshlrev_b32_e32 v130, 16, v120
	v_and_b32_e32 v131, 0xffff0000, v120
	v_lshlrev_b32_e32 v132, 16, v121
	v_and_b32_e32 v133, 0xffff0000, v121
	v_lshlrev_b32_e32 v134, 16, v122
	v_and_b32_e32 v135, 0xffff0000, v122
	v_lshlrev_b32_e32 v136, 16, v123
	v_and_b32_e32 v137, 0xffff0000, v123
	v_lshlrev_b32_e32 v138, 16, v124
	v_and_b32_e32 v139, 0xffff0000, v124
	v_lshlrev_b32_e32 v140, 16, v125
	v_and_b32_e32 v141, 0xffff0000, v125
	v_lshlrev_b32_e32 v142, 16, v126
	v_and_b32_e32 v143, 0xffff0000, v126
	v_lshlrev_b32_e32 v144, 16, v127
	v_and_b32_e32 v145, 0xffff0000, v127
	v_lshlrev_b32_e32 v146, 16, v128
	v_and_b32_e32 v147, 0xffff0000, v128
	v_lshlrev_b32_e32 v148, 16, v129
	v_and_b32_e32 v149, 0xffff0000, v129
	v_pk_add_f32 v[158:159], v[84:85], v[130:131] neg_lo:[0,1] neg_hi:[0,1]
	v_pk_add_f32 v[160:161], v[86:87], v[132:133] neg_lo:[0,1] neg_hi:[0,1]
	v_pk_fma_f32 v[130:131], v[158:159], v[96:97], v[130:131]
	v_pk_fma_f32 v[132:133], v[160:161], v[98:99], v[132:133]
	v_pk_add_f32 v[158:159], v[88:89], v[134:135] neg_lo:[0,1] neg_hi:[0,1]
	v_pk_add_f32 v[160:161], v[90:91], v[136:137] neg_lo:[0,1] neg_hi:[0,1]
	v_pk_fma_f32 v[134:135], v[158:159], v[100:101], v[134:135]
	v_pk_fma_f32 v[136:137], v[160:161], v[102:103], v[136:137]
	v_pk_add_f32 v[158:159], v[92:93], v[138:139] neg_lo:[0,1] neg_hi:[0,1]
	v_pk_add_f32 v[160:161], v[94:95], v[140:141] neg_lo:[0,1] neg_hi:[0,1]
	v_pk_fma_f32 v[138:139], v[158:159], v[104:105], v[138:139]
	v_pk_fma_f32 v[140:141], v[160:161], v[106:107], v[140:141]
	v_pk_mul_f32 v[150:151], v[134:135], v[108:109]
	v_pk_mul_f32 v[152:153], v[136:137], v[110:111]
	v_pk_add_f32 v[158:159], v[146:147], -1.0 op_sel_hi:[1,0]
	v_pk_add_f32 v[160:161], v[148:149], -1.0 op_sel_hi:[1,0]
	v_pk_fma_f32 v[158:159], v[112:113], v[158:159], 1.0 op_sel_hi:[1,1,0]
	v_pk_fma_f32 v[160:161], v[114:115], v[160:161], 1.0 op_sel_hi:[1,1,0]
	v_pk_mul_f32 v[154:155], v[134:135], v[158:159]
	v_pk_mul_f32 v[156:157], v[136:137], v[160:161]
	v_pk_mul_f32 v[158:159], v[130:131], v[154:155]
	v_pk_mul_f32 v[160:161], v[132:133], v[156:157]
	v_pk_mul_f32 v[162:163], v[158:159], v[116:117]
	v_pk_mul_f32 v[164:165], v[160:161], v[118:119]
	v_pk_add_f32 v[162:163], v[162:163], v[164:165]
	v_pk_mul_f32 v[158:159], v[150:151], v[150:151]
	v_pk_mul_f32 v[160:161], v[152:153], v[152:153]
	v_add_f32_e32 v167, v162, v163
	v_pk_add_f32 v[158:159], v[158:159], v[160:161]
	v_mul_f32_e32 v142, 0x3fb8aa3b, v142
	v_mul_f32_e32 v143, 0x3fb8aa3b, v143
	v_mul_f32_e32 v144, 0x3fb8aa3b, v144
	v_mul_f32_e32 v145, 0x3fb8aa3b, v145
	v_add_f32_e32 v166, v158, v159
	v_exp_f32_e32 v142, v142
	v_exp_f32_e32 v143, v143
	v_exp_f32_e32 v144, v144
	v_exp_f32_e32 v145, v145
	v_add_f32_dpp v166, v166, v166 quad_perm:[1,0,3,2] row_mask:0xf bank_mask:0xf bound_ctrl:1
	v_add_f32_dpp v167, v167, v167 quad_perm:[1,0,3,2] row_mask:0xf bank_mask:0xf bound_ctrl:1
	s_nop 0
	v_add_f32_dpp v166, v166, v166 quad_perm:[2,3,0,1] row_mask:0xf bank_mask:0xf bound_ctrl:1
	v_add_f32_dpp v167, v167, v167 quad_perm:[2,3,0,1] row_mask:0xf bank_mask:0xf bound_ctrl:1
	s_nop 0
	v_add_f32_dpp v166, v166, v166 row_half_mirror row_mask:0xf bank_mask:0xf bound_ctrl:1
	v_add_f32_dpp v167, v167, v167 row_half_mirror row_mask:0xf bank_mask:0xf bound_ctrl:1
	s_nop 0
	v_add_f32_dpp v166, v166, v166 row_ror:8 row_mask:0xf bank_mask:0xf bound_ctrl:1
	v_add_f32_dpp v167, v167, v167 row_ror:8 row_mask:0xf bank_mask:0xf bound_ctrl:1
	v_rsq_f32_e32 v168, v166
	v_mul_u32_u24_e32 v173, 0x600, v172
	v_lshl_add_u32 v173, v174, 4, v173
	v_add_u32_e32 v173, 0x1d000, v173
	v_min_f32_e32 v168, 0x5368d4a5, v168
	v_pk_mul_f32 v[158:159], v[150:151], v[168:169] op_sel_hi:[1,0] neg_lo:[1,0] neg_hi:[1,0]
	v_pk_mul_f32 v[160:161], v[152:153], v[168:169] op_sel_hi:[1,0] neg_lo:[1,0] neg_hi:[1,0]
	v_pk_mul_f32 v[162:163], v[150:151], v[168:169] op_sel_hi:[1,0]
	v_pk_mul_f32 v[164:165], v[152:153], v[168:169] op_sel_hi:[1,0]
	v_pk_mul_f32 v[162:163], v[162:163], v[146:147]
	v_pk_mul_f32 v[164:165], v[164:165], v[148:149]
	v_lshlrev_b32_e32 v172, 2, v172
	v_add_u32_e32 v172, 0x1ac00, v172
	ds_write_b128 v173, v[130:133]
	ds_write_b128 v173, v[142:145] offset:256
	ds_write_b128 v173, v[154:157] offset:512
	ds_write_b128 v173, v[158:161] offset:768
	ds_write_b128 v173, v[162:165] offset:1024
	ds_write_b128 v173, v[138:141] offset:1280
	ds_write_b32 v172, v167
.Lhs_p1c_skip:
	v_cmp_ne_u32_e64 s[6:7], 0, v206
	s_nop 3
	v_cndmask_b32_e64 v64, 0, v64, s[6:7]
	v_cndmask_b32_e64 v65, 0, v65, s[6:7]
	v_cndmask_b32_e64 v66, 0, v66, s[6:7]
	v_cndmask_b32_e64 v67, 0, v67, s[6:7]
	v_cndmask_b32_e64 v68, 0, v68, s[6:7]
	v_cndmask_b32_e64 v69, 0, v69, s[6:7]
	v_cndmask_b32_e64 v70, 0, v70, s[6:7]
	v_cndmask_b32_e64 v71, 0, v71, s[6:7]
	v_cndmask_b32_e64 v72, 0, v72, s[6:7]
	v_cndmask_b32_e64 v73, 0, v73, s[6:7]
	v_cndmask_b32_e64 v74, 0, v74, s[6:7]
	v_cndmask_b32_e64 v75, 0, v75, s[6:7]
	v_lshlrev_b32_e32 v84, 16, v52
	v_and_b32_e32 v85, 0xffff0000, v52
	v_lshlrev_b32_e32 v86, 16, v53
	v_and_b32_e32 v87, 0xffff0000, v53
	v_lshlrev_b32_e32 v88, 16, v54
	v_and_b32_e32 v89, 0xffff0000, v54
	v_lshlrev_b32_e32 v90, 16, v55
	v_and_b32_e32 v91, 0xffff0000, v55
	v_lshlrev_b32_e32 v124, 16, v64
	v_and_b32_e32 v125, 0xffff0000, v64
	v_lshlrev_b32_e32 v126, 16, v65
	v_and_b32_e32 v127, 0xffff0000, v65
	v_lshlrev_b32_e32 v128, 16, v66
	v_and_b32_e32 v129, 0xffff0000, v66
	v_lshlrev_b32_e32 v130, 16, v67
	v_and_b32_e32 v131, 0xffff0000, v67
	v_pk_add_f32 v[124:125], v[124:125], v[84:85] neg_lo:[0,1] neg_hi:[0,1]
	v_pk_add_f32 v[126:127], v[126:127], v[86:87] neg_lo:[0,1] neg_hi:[0,1]
	v_pk_add_f32 v[128:129], v[128:129], v[88:89] neg_lo:[0,1] neg_hi:[0,1]
	v_pk_add_f32 v[130:131], v[130:131], v[90:91] neg_lo:[0,1] neg_hi:[0,1]
	v_pk_fma_f32 v[84:85], v[0:1], v[124:125], v[84:85]
	v_pk_fma_f32 v[86:87], v[2:3], v[126:127], v[86:87]
	v_pk_fma_f32 v[88:89], v[4:5], v[128:129], v[88:89]
	v_pk_fma_f32 v[90:91], v[6:7], v[130:131], v[90:91]
	v_lshlrev_b32_e32 v92, 16, v56
	v_and_b32_e32 v93, 0xffff0000, v56
	v_lshlrev_b32_e32 v94, 16, v57
	v_and_b32_e32 v95, 0xffff0000, v57
	v_lshlrev_b32_e32 v96, 16, v58
	v_and_b32_e32 v97, 0xffff0000, v58
	v_lshlrev_b32_e32 v98, 16, v59
	v_and_b32_e32 v99, 0xffff0000, v59
	v_lshlrev_b32_e32 v124, 16, v68
	v_and_b32_e32 v125, 0xffff0000, v68
	v_lshlrev_b32_e32 v126, 16, v69
	v_and_b32_e32 v127, 0xffff0000, v69
	v_lshlrev_b32_e32 v128, 16, v70
	v_and_b32_e32 v129, 0xffff0000, v70
	v_lshlrev_b32_e32 v130, 16, v71
	v_and_b32_e32 v131, 0xffff0000, v71
	v_pk_add_f32 v[124:125], v[124:125], v[92:93] neg_lo:[0,1] neg_hi:[0,1]
	v_pk_add_f32 v[126:127], v[126:127], v[94:95] neg_lo:[0,1] neg_hi:[0,1]
	v_pk_add_f32 v[128:129], v[128:129], v[96:97] neg_lo:[0,1] neg_hi:[0,1]
	v_pk_add_f32 v[130:131], v[130:131], v[98:99] neg_lo:[0,1] neg_hi:[0,1]
	v_pk_fma_f32 v[92:93], v[8:9], v[124:125], v[92:93]
	v_pk_fma_f32 v[94:95], v[10:11], v[126:127], v[94:95]
	v_pk_fma_f32 v[96:97], v[12:13], v[128:129], v[96:97]
	v_pk_fma_f32 v[98:99], v[14:15], v[130:131], v[98:99]
	v_lshlrev_b32_e32 v100, 16, v60
	v_and_b32_e32 v101, 0xffff0000, v60
	v_lshlrev_b32_e32 v102, 16, v61
	v_and_b32_e32 v103, 0xffff0000, v61
	v_lshlrev_b32_e32 v104, 16, v62
	v_and_b32_e32 v105, 0xffff0000, v62
	v_lshlrev_b32_e32 v106, 16, v63
	v_and_b32_e32 v107, 0xffff0000, v63
	v_lshlrev_b32_e32 v124, 16, v72
	v_and_b32_e32 v125, 0xffff0000, v72
	v_lshlrev_b32_e32 v126, 16, v73
	v_and_b32_e32 v127, 0xffff0000, v73
	v_lshlrev_b32_e32 v128, 16, v74
	v_and_b32_e32 v129, 0xffff0000, v74
	v_lshlrev_b32_e32 v130, 16, v75
	v_and_b32_e32 v131, 0xffff0000, v75
	v_pk_add_f32 v[124:125], v[124:125], v[100:101] neg_lo:[0,1] neg_hi:[0,1]
	v_pk_add_f32 v[126:127], v[126:127], v[102:103] neg_lo:[0,1] neg_hi:[0,1]
	v_pk_add_f32 v[128:129], v[128:129], v[104:105] neg_lo:[0,1] neg_hi:[0,1]
	v_pk_add_f32 v[130:131], v[130:131], v[106:107] neg_lo:[0,1] neg_hi:[0,1]
	v_pk_fma_f32 v[100:101], v[16:17], v[124:125], v[100:101]
	v_pk_fma_f32 v[102:103], v[18:19], v[126:127], v[102:103]
	v_pk_fma_f32 v[104:105], v[20:21], v[128:129], v[104:105]
	v_pk_fma_f32 v[106:107], v[22:23], v[130:131], v[106:107]
	v_lshlrev_b32_e32 v108, 16, v80
	v_and_b32_e32 v109, 0xffff0000, v80
	v_lshlrev_b32_e32 v110, 16, v81
	v_and_b32_e32 v111, 0xffff0000, v81
	v_lshlrev_b32_e32 v112, 16, v82
	v_and_b32_e32 v113, 0xffff0000, v82
	v_lshlrev_b32_e32 v114, 16, v83
	v_and_b32_e32 v115, 0xffff0000, v83
	v_lshlrev_b32_e32 v116, 16, v76
	v_and_b32_e32 v117, 0xffff0000, v76
	v_lshlrev_b32_e32 v118, 16, v77
	v_and_b32_e32 v119, 0xffff0000, v77
	v_lshlrev_b32_e32 v120, 16, v78
	v_and_b32_e32 v121, 0xffff0000, v78
	v_lshlrev_b32_e32 v122, 16, v79
	v_and_b32_e32 v123, 0xffff0000, v79
	v_pk_mul_f32 v[132:133], v[92:93], v[24:25]
	v_pk_mul_f32 v[134:135], v[94:95], v[26:27]
	v_pk_mul_f32 v[136:137], v[96:97], v[28:29]
	v_pk_mul_f32 v[138:139], v[98:99], v[30:31]
	v_pk_add_f32 v[124:125], v[108:109], -1.0 op_sel_hi:[1,0]
	v_pk_add_f32 v[126:127], v[110:111], -1.0 op_sel_hi:[1,0]
	v_pk_add_f32 v[128:129], v[112:113], -1.0 op_sel_hi:[1,0]
	v_pk_add_f32 v[130:131], v[114:115], -1.0 op_sel_hi:[1,0]
	v_pk_fma_f32 v[124:125], v[32:33], v[124:125], 1.0 op_sel_hi:[1,1,0]
	v_pk_fma_f32 v[126:127], v[34:35], v[126:127], 1.0 op_sel_hi:[1,1,0]
	v_pk_fma_f32 v[128:129], v[36:37], v[128:129], 1.0 op_sel_hi:[1,1,0]
	v_pk_fma_f32 v[130:131], v[38:39], v[130:131], 1.0 op_sel_hi:[1,1,0]
	v_pk_mul_f32 v[140:141], v[124:125], v[92:93]
	v_pk_mul_f32 v[142:143], v[126:127], v[94:95]
	v_pk_mul_f32 v[144:145], v[128:129], v[96:97]
	v_pk_mul_f32 v[146:147], v[130:131], v[98:99]
	v_pk_mul_f32 v[148:149], v[84:85], v[140:141]
	v_pk_mul_f32 v[150:151], v[86:87], v[142:143]
	v_pk_mul_f32 v[152:153], v[88:89], v[144:145]
	v_pk_mul_f32 v[154:155], v[90:91], v[146:147]
	v_pk_mul_f32 v[156:157], v[132:133], v[108:109]
	v_pk_mul_f32 v[158:159], v[134:135], v[110:111]
	v_pk_mul_f32 v[160:161], v[136:137], v[112:113]
	v_pk_mul_f32 v[162:163], v[138:139], v[114:115]
	v_pk_mul_f32 v[124:125], v[148:149], v[40:41]
	v_pk_mul_f32 v[126:127], v[150:151], v[42:43]
	v_pk_mul_f32 v[128:129], v[152:153], v[44:45]
	v_pk_mul_f32 v[130:131], v[154:155], v[46:47]
	v_pk_add_f32 v[124:125], v[124:125], v[126:127]
	v_pk_add_f32 v[128:129], v[128:129], v[130:131]
	v_pk_add_f32 v[124:125], v[124:125], v[128:129]
	v_add_f32_e32 v173, v124, v125
	v_pk_mul_f32 v[124:125], v[156:157], v[84:85]
	v_pk_mul_f32 v[126:127], v[158:159], v[86:87]
	v_pk_mul_f32 v[128:129], v[160:161], v[88:89]
	v_pk_mul_f32 v[130:131], v[162:163], v[90:91]
	v_pk_add_f32 v[124:125], v[124:125], v[126:127]
	v_pk_add_f32 v[128:129], v[128:129], v[130:131]
	v_pk_add_f32 v[124:125], v[124:125], v[128:129]
	v_add_f32_e32 v174, v124, v125
	v_pk_mul_f32 v[124:125], v[132:133], v[132:133]
	v_pk_mul_f32 v[126:127], v[134:135], v[134:135]
	v_pk_mul_f32 v[128:129], v[136:137], v[136:137]
	v_pk_mul_f32 v[130:131], v[138:139], v[138:139]
	v_pk_add_f32 v[124:125], v[124:125], v[126:127]
	v_pk_add_f32 v[128:129], v[128:129], v[130:131]
	v_pk_add_f32 v[124:125], v[124:125], v[128:129]
	v_add_f32_e32 v172, v124, v125
	v_pk_add_f32 v[148:149], v[148:149], v[150:151]
	v_pk_add_f32 v[152:153], v[152:153], v[154:155]
	v_pk_add_f32 v[148:149], v[148:149], v[152:153]
	v_add_f32_e32 v175, v148, v149
	v_pk_mul_f32 v[116:117], v[116:117], v[48:49]
	v_pk_mul_f32 v[118:119], v[118:119], v[48:49]
	v_pk_mul_f32 v[120:121], v[120:121], v[48:49]
	v_pk_mul_f32 v[122:123], v[122:123], v[48:49]
	v_add_f32_dpp v172, v172, v172 quad_perm:[1,0,3,2] row_mask:0xf bank_mask:0xf bound_ctrl:1
	v_add_f32_dpp v173, v173, v173 quad_perm:[1,0,3,2] row_mask:0xf bank_mask:0xf bound_ctrl:1
	v_add_f32_dpp v174, v174, v174 quad_perm:[1,0,3,2] row_mask:0xf bank_mask:0xf bound_ctrl:1
	v_add_f32_dpp v175, v175, v175 quad_perm:[1,0,3,2] row_mask:0xf bank_mask:0xf bound_ctrl:1
	v_add_f32_dpp v172, v172, v172 quad_perm:[2,3,0,1] row_mask:0xf bank_mask:0xf bound_ctrl:1
	v_add_f32_dpp v173, v173, v173 quad_perm:[2,3,0,1] row_mask:0xf bank_mask:0xf bound_ctrl:1
	v_add_f32_dpp v174, v174, v174 quad_perm:[2,3,0,1] row_mask:0xf bank_mask:0xf bound_ctrl:1
	v_add_f32_dpp v175, v175, v175 quad_perm:[2,3,0,1] row_mask:0xf bank_mask:0xf bound_ctrl:1
	v_add_f32_dpp v172, v172, v172 row_half_mirror row_mask:0xf bank_mask:0xf bound_ctrl:1
	v_add_f32_dpp v173, v173, v173 row_half_mirror row_mask:0xf bank_mask:0xf bound_ctrl:1
	v_add_f32_dpp v174, v174, v174 row_half_mirror row_mask:0xf bank_mask:0xf bound_ctrl:1
	v_add_f32_dpp v175, v175, v175 row_half_mirror row_mask:0xf bank_mask:0xf bound_ctrl:1
	v_exp_f32_e32 v116, v116
	v_exp_f32_e32 v117, v117
	v_exp_f32_e32 v118, v118
	v_exp_f32_e32 v119, v119
	v_exp_f32_e32 v120, v120
	v_exp_f32_e32 v121, v121
	v_exp_f32_e32 v122, v122
	v_exp_f32_e32 v123, v123
	v_rsq_f32_e32 v176, v172
	v_pk_mul_f32 v[148:149], v[116:117], v[84:85]
	v_pk_mul_f32 v[150:151], v[118:119], v[86:87]
	v_pk_mul_f32 v[152:153], v[120:121], v[88:89]
	v_pk_mul_f32 v[154:155], v[122:123], v[90:91]
	v_min_f32_e32 v176, 0x5368d4a5, v176
	v_mul_f32_e32 v174, v174, v176
	v_pk_mul_f32 v[164:165], v[132:133], v[176:177] op_sel_hi:[1,0] neg_lo:[1,0] neg_hi:[1,0]
	v_pk_mul_f32 v[166:167], v[134:135], v[176:177] op_sel_hi:[1,0] neg_lo:[1,0] neg_hi:[1,0]
	v_pk_mul_f32 v[168:169], v[136:137], v[176:177] op_sel_hi:[1,0] neg_lo:[1,0] neg_hi:[1,0]
	v_pk_mul_f32 v[170:171], v[138:139], v[176:177] op_sel_hi:[1,0] neg_lo:[1,0] neg_hi:[1,0]
	v_pk_mul_f32 v[156:157], v[156:157], v[176:177] op_sel_hi:[1,0]
	v_pk_mul_f32 v[158:159], v[158:159], v[176:177] op_sel_hi:[1,0]
	v_pk_mul_f32 v[160:161], v[160:161], v[176:177] op_sel_hi:[1,0]
	v_pk_mul_f32 v[162:163], v[162:163], v[176:177] op_sel_hi:[1,0]
	s_mul_i32 s14, s13, 0xc000
	v_add_u32_e32 v198, s14, v194
	ds_write_b128 v198, v[148:151] offset:0
	ds_write_b128 v198, v[152:155] offset:128
	ds_write_b128 v198, v[116:119] offset:256
	ds_write_b128 v198, v[120:123] offset:384
	ds_write_b128 v198, v[140:143] offset:512
	ds_write_b128 v198, v[144:147] offset:640
	ds_write_b128 v198, v[164:167] offset:768
	ds_write_b128 v198, v[168:171] offset:896
	ds_write_b128 v198, v[156:159] offset:1024
	ds_write_b128 v198, v[160:163] offset:1152
	ds_write_b128 v198, v[100:103] offset:1280
	ds_write_b128 v198, v[104:107] offset:1408
	s_lshl_b32 s14, s13, 7
	v_add_u32_e32 v199, s14, v196
	s_lshl_b32 s14, s13, 8
	v_add_u32_e32 v198, s14, v197
	ds_write_b32 v199, v173
	ds_write_b64 v198, v[174:175]
	s_mov_b64 s[0:1], 0x34000
	v_lshl_add_u64 v[178:179], v[178:179], 0, s[0:1]
	v_lshl_add_u64 v[180:181], v[180:181], 0, s[0:1]
	v_lshl_add_u64 v[182:183], v[182:183], 0, s[0:1]
	s_mov_b64 s[0:1], 0x10000
	v_lshl_add_u64 v[186:187], v[186:187], 0, s[0:1]
	v_lshl_add_u64 v[188:189], v[188:189], 0, s[0:1]
	global_load_dwordx2 v[52:53], v[178:179], off
	global_load_dwordx2 v[54:55], v[178:179], off offset:64
	global_load_dwordx2 v[56:57], v[178:179], off offset:2048
	global_load_dwordx2 v[58:59], v[178:179], off offset:2112
	global_load_dwordx2 v[60:61], v[180:181], off
	global_load_dwordx2 v[62:63], v[180:181], off offset:64
	global_load_dwordx2 v[64:65], v[182:183], off offset:-2560
	global_load_dwordx2 v[66:67], v[182:183], off offset:-2496
	global_load_dwordx2 v[68:69], v[182:183], off offset:-512
	global_load_dwordx2 v[70:71], v[182:183], off offset:-448
	global_load_dwordx2 v[72:73], v[178:179], off offset:-2560
	global_load_dwordx2 v[74:75], v[178:179], off offset:-2496
	global_load_dwordx2 v[76:77], v[186:187], off
	global_load_dwordx2 v[78:79], v[186:187], off offset:64
	global_load_dwordx2 v[80:81], v[188:189], off
	global_load_dwordx2 v[82:83], v[188:189], off offset:64
	s_waitcnt lgkmcnt(0)
	s_barrier
	s_waitcnt vmcnt(0)
	s_mov_b32 s12, 0

.Lh_nopost:
	s_cmp_lt_u32 s12, 64
	s_cbranch_scc0 .Lh_nobuild
	s_add_i32 s13, s12, 1
	s_and_b32 s13, s13, 1
	s_waitcnt vmcnt(1)
	v_lshlrev_b32_e32 v84, 16, v52
	v_and_b32_e32 v85, 0xffff0000, v52
	v_lshlrev_b32_e32 v86, 16, v53
	v_and_b32_e32 v87, 0xffff0000, v53
	v_lshlrev_b32_e32 v88, 16, v54
	v_and_b32_e32 v89, 0xffff0000, v54
	v_lshlrev_b32_e32 v90, 16, v55
	v_and_b32_e32 v91, 0xffff0000, v55
	v_lshlrev_b32_e32 v124, 16, v64
	v_and_b32_e32 v125, 0xffff0000, v64
	v_lshlrev_b32_e32 v126, 16, v65
	v_and_b32_e32 v127, 0xffff0000, v65
	v_lshlrev_b32_e32 v128, 16, v66
	v_and_b32_e32 v129, 0xffff0000, v66
	v_lshlrev_b32_e32 v130, 16, v67
	v_and_b32_e32 v131, 0xffff0000, v67
	v_pk_add_f32 v[124:125], v[124:125], v[84:85] neg_lo:[0,1] neg_hi:[0,1]
	v_pk_add_f32 v[126:127], v[126:127], v[86:87] neg_lo:[0,1] neg_hi:[0,1]
	v_pk_add_f32 v[128:129], v[128:129], v[88:89] neg_lo:[0,1] neg_hi:[0,1]
	v_pk_add_f32 v[130:131], v[130:131], v[90:91] neg_lo:[0,1] neg_hi:[0,1]
	v_pk_fma_f32 v[84:85], v[0:1], v[124:125], v[84:85]
	v_pk_fma_f32 v[86:87], v[2:3], v[126:127], v[86:87]
	v_pk_fma_f32 v[88:89], v[4:5], v[128:129], v[88:89]
	v_pk_fma_f32 v[90:91], v[6:7], v[130:131], v[90:91]
	v_lshlrev_b32_e32 v92, 16, v56
	v_and_b32_e32 v93, 0xffff0000, v56
	v_lshlrev_b32_e32 v94, 16, v57
	v_and_b32_e32 v95, 0xffff0000, v57
	v_lshlrev_b32_e32 v96, 16, v58
	v_and_b32_e32 v97, 0xffff0000, v58
	v_lshlrev_b32_e32 v98, 16, v59
	v_and_b32_e32 v99, 0xffff0000, v59
	v_lshlrev_b32_e32 v124, 16, v68
	v_and_b32_e32 v125, 0xffff0000, v68
	v_lshlrev_b32_e32 v126, 16, v69
	v_and_b32_e32 v127, 0xffff0000, v69
	v_lshlrev_b32_e32 v128, 16, v70
	v_and_b32_e32 v129, 0xffff0000, v70
	v_lshlrev_b32_e32 v130, 16, v71
	v_and_b32_e32 v131, 0xffff0000, v71
	v_pk_add_f32 v[124:125], v[124:125], v[92:93] neg_lo:[0,1] neg_hi:[0,1]
	v_pk_add_f32 v[126:127], v[126:127], v[94:95] neg_lo:[0,1] neg_hi:[0,1]
	v_pk_add_f32 v[128:129], v[128:129], v[96:97] neg_lo:[0,1] neg_hi:[0,1]
	v_pk_add_f32 v[130:131], v[130:131], v[98:99] neg_lo:[0,1] neg_hi:[0,1]
	v_pk_fma_f32 v[92:93], v[8:9], v[124:125], v[92:93]
	v_pk_fma_f32 v[94:95], v[10:11], v[126:127], v[94:95]
	v_pk_fma_f32 v[96:97], v[12:13], v[128:129], v[96:97]
	v_pk_fma_f32 v[98:99], v[14:15], v[130:131], v[98:99]
	v_lshlrev_b32_e32 v100, 16, v60
	v_and_b32_e32 v101, 0xffff0000, v60
	v_lshlrev_b32_e32 v102, 16, v61
	v_and_b32_e32 v103, 0xffff0000, v61
	v_lshlrev_b32_e32 v104, 16, v62
	v_and_b32_e32 v105, 0xffff0000, v62
	v_lshlrev_b32_e32 v106, 16, v63
	v_and_b32_e32 v107, 0xffff0000, v63
	v_lshlrev_b32_e32 v124, 16, v72
	v_and_b32_e32 v125, 0xffff0000, v72
	v_lshlrev_b32_e32 v126, 16, v73
	v_and_b32_e32 v127, 0xffff0000, v73
	v_lshlrev_b32_e32 v128, 16, v74
	v_and_b32_e32 v129, 0xffff0000, v74
	v_lshlrev_b32_e32 v130, 16, v75
	v_and_b32_e32 v131, 0xffff0000, v75
	v_pk_add_f32 v[124:125], v[124:125], v[100:101] neg_lo:[0,1] neg_hi:[0,1]
	v_pk_add_f32 v[126:127], v[126:127], v[102:103] neg_lo:[0,1] neg_hi:[0,1]
	v_pk_add_f32 v[128:129], v[128:129], v[104:105] neg_lo:[0,1] neg_hi:[0,1]
	v_pk_add_f32 v[130:131], v[130:131], v[106:107] neg_lo:[0,1] neg_hi:[0,1]
	v_pk_fma_f32 v[100:101], v[16:17], v[124:125], v[100:101]
	v_pk_fma_f32 v[102:103], v[18:19], v[126:127], v[102:103]
	v_pk_fma_f32 v[104:105], v[20:21], v[128:129], v[104:105]
	v_pk_fma_f32 v[106:107], v[22:23], v[130:131], v[106:107]
	v_lshlrev_b32_e32 v108, 16, v80
	v_and_b32_e32 v109, 0xffff0000, v80
	v_lshlrev_b32_e32 v110, 16, v81
	v_and_b32_e32 v111, 0xffff0000, v81
	v_lshlrev_b32_e32 v112, 16, v82
	v_and_b32_e32 v113, 0xffff0000, v82
	v_lshlrev_b32_e32 v114, 16, v83
	v_and_b32_e32 v115, 0xffff0000, v83
	v_lshlrev_b32_e32 v116, 16, v76
	v_and_b32_e32 v117, 0xffff0000, v76
	v_lshlrev_b32_e32 v118, 16, v77
	v_and_b32_e32 v119, 0xffff0000, v77
	v_lshlrev_b32_e32 v120, 16, v78
	v_and_b32_e32 v121, 0xffff0000, v78
	v_lshlrev_b32_e32 v122, 16, v79
	v_and_b32_e32 v123, 0xffff0000, v79
	v_pk_mul_f32 v[132:133], v[92:93], v[24:25]
	v_pk_mul_f32 v[134:135], v[94:95], v[26:27]
	v_pk_mul_f32 v[136:137], v[96:97], v[28:29]
	v_pk_mul_f32 v[138:139], v[98:99], v[30:31]
	v_pk_add_f32 v[124:125], v[108:109], -1.0 op_sel_hi:[1,0]
	v_pk_add_f32 v[126:127], v[110:111], -1.0 op_sel_hi:[1,0]
	v_pk_add_f32 v[128:129], v[112:113], -1.0 op_sel_hi:[1,0]
	v_pk_add_f32 v[130:131], v[114:115], -1.0 op_sel_hi:[1,0]
	v_pk_fma_f32 v[124:125], v[32:33], v[124:125], 1.0 op_sel_hi:[1,1,0]
	v_pk_fma_f32 v[126:127], v[34:35], v[126:127], 1.0 op_sel_hi:[1,1,0]
	v_pk_fma_f32 v[128:129], v[36:37], v[128:129], 1.0 op_sel_hi:[1,1,0]
	v_pk_fma_f32 v[130:131], v[38:39], v[130:131], 1.0 op_sel_hi:[1,1,0]
	v_pk_mul_f32 v[140:141], v[124:125], v[92:93]
	v_pk_mul_f32 v[142:143], v[126:127], v[94:95]
	v_pk_mul_f32 v[144:145], v[128:129], v[96:97]
	v_pk_mul_f32 v[146:147], v[130:131], v[98:99]
	v_pk_mul_f32 v[148:149], v[84:85], v[140:141]
	v_pk_mul_f32 v[150:151], v[86:87], v[142:143]
	v_pk_mul_f32 v[152:153], v[88:89], v[144:145]
	v_pk_mul_f32 v[154:155], v[90:91], v[146:147]
	v_pk_mul_f32 v[156:157], v[132:133], v[108:109]
	v_pk_mul_f32 v[158:159], v[134:135], v[110:111]
	v_pk_mul_f32 v[160:161], v[136:137], v[112:113]
	v_pk_mul_f32 v[162:163], v[138:139], v[114:115]
	v_pk_mul_f32 v[124:125], v[148:149], v[40:41]
	v_pk_mul_f32 v[126:127], v[150:151], v[42:43]
	v_pk_mul_f32 v[128:129], v[152:153], v[44:45]
	v_pk_mul_f32 v[130:131], v[154:155], v[46:47]
	v_pk_add_f32 v[124:125], v[124:125], v[126:127]
	v_pk_add_f32 v[128:129], v[128:129], v[130:131]
	v_pk_add_f32 v[124:125], v[124:125], v[128:129]
	v_add_f32_e32 v173, v124, v125
	v_pk_mul_f32 v[124:125], v[156:157], v[84:85]
	v_pk_mul_f32 v[126:127], v[158:159], v[86:87]
	v_pk_mul_f32 v[128:129], v[160:161], v[88:89]
	v_pk_mul_f32 v[130:131], v[162:163], v[90:91]
	v_pk_add_f32 v[124:125], v[124:125], v[126:127]
	v_pk_add_f32 v[128:129], v[128:129], v[130:131]
	v_pk_add_f32 v[124:125], v[124:125], v[128:129]
	v_add_f32_e32 v174, v124, v125
	v_pk_mul_f32 v[124:125], v[132:133], v[132:133]
	v_pk_mul_f32 v[126:127], v[134:135], v[134:135]
	v_pk_mul_f32 v[128:129], v[136:137], v[136:137]
	v_pk_mul_f32 v[130:131], v[138:139], v[138:139]
	v_pk_add_f32 v[124:125], v[124:125], v[126:127]
	v_pk_add_f32 v[128:129], v[128:129], v[130:131]
	v_pk_add_f32 v[124:125], v[124:125], v[128:129]
	v_add_f32_e32 v172, v124, v125
	v_pk_add_f32 v[148:149], v[148:149], v[150:151]
	v_pk_add_f32 v[152:153], v[152:153], v[154:155]
	v_pk_add_f32 v[148:149], v[148:149], v[152:153]
	v_add_f32_e32 v175, v148, v149
	v_pk_mul_f32 v[116:117], v[116:117], v[48:49]
	v_pk_mul_f32 v[118:119], v[118:119], v[48:49]
	v_pk_mul_f32 v[120:121], v[120:121], v[48:49]
	v_pk_mul_f32 v[122:123], v[122:123], v[48:49]
	v_add_f32_dpp v172, v172, v172 quad_perm:[1,0,3,2] row_mask:0xf bank_mask:0xf bound_ctrl:1
	v_add_f32_dpp v173, v173, v173 quad_perm:[1,0,3,2] row_mask:0xf bank_mask:0xf bound_ctrl:1
	v_add_f32_dpp v174, v174, v174 quad_perm:[1,0,3,2] row_mask:0xf bank_mask:0xf bound_ctrl:1
	v_add_f32_dpp v175, v175, v175 quad_perm:[1,0,3,2] row_mask:0xf bank_mask:0xf bound_ctrl:1
	v_add_f32_dpp v172, v172, v172 quad_perm:[2,3,0,1] row_mask:0xf bank_mask:0xf bound_ctrl:1
	v_add_f32_dpp v173, v173, v173 quad_perm:[2,3,0,1] row_mask:0xf bank_mask:0xf bound_ctrl:1
	v_add_f32_dpp v174, v174, v174 quad_perm:[2,3,0,1] row_mask:0xf bank_mask:0xf bound_ctrl:1
	v_add_f32_dpp v175, v175, v175 quad_perm:[2,3,0,1] row_mask:0xf bank_mask:0xf bound_ctrl:1
	v_add_f32_dpp v172, v172, v172 row_half_mirror row_mask:0xf bank_mask:0xf bound_ctrl:1
	v_add_f32_dpp v173, v173, v173 row_half_mirror row_mask:0xf bank_mask:0xf bound_ctrl:1
	v_add_f32_dpp v174, v174, v174 row_half_mirror row_mask:0xf bank_mask:0xf bound_ctrl:1
	v_add_f32_dpp v175, v175, v175 row_half_mirror row_mask:0xf bank_mask:0xf bound_ctrl:1
	v_exp_f32_e32 v116, v116
	v_exp_f32_e32 v117, v117
	v_exp_f32_e32 v118, v118
	v_exp_f32_e32 v119, v119
	v_exp_f32_e32 v120, v120
	v_exp_f32_e32 v121, v121
	v_exp_f32_e32 v122, v122
	v_exp_f32_e32 v123, v123
	v_rsq_f32_e32 v176, v172
	v_pk_mul_f32 v[148:149], v[116:117], v[84:85]
	v_pk_mul_f32 v[150:151], v[118:119], v[86:87]
	v_pk_mul_f32 v[152:153], v[120:121], v[88:89]
	v_pk_mul_f32 v[154:155], v[122:123], v[90:91]
	v_min_f32_e32 v176, 0x5368d4a5, v176
	v_mul_f32_e32 v174, v174, v176
	v_pk_mul_f32 v[164:165], v[132:133], v[176:177] op_sel_hi:[1,0] neg_lo:[1,0] neg_hi:[1,0]
	v_pk_mul_f32 v[166:167], v[134:135], v[176:177] op_sel_hi:[1,0] neg_lo:[1,0] neg_hi:[1,0]
	v_pk_mul_f32 v[168:169], v[136:137], v[176:177] op_sel_hi:[1,0] neg_lo:[1,0] neg_hi:[1,0]
	v_pk_mul_f32 v[170:171], v[138:139], v[176:177] op_sel_hi:[1,0] neg_lo:[1,0] neg_hi:[1,0]
	v_pk_mul_f32 v[156:157], v[156:157], v[176:177] op_sel_hi:[1,0]
	v_pk_mul_f32 v[158:159], v[158:159], v[176:177] op_sel_hi:[1,0]
	v_pk_mul_f32 v[160:161], v[160:161], v[176:177] op_sel_hi:[1,0]
	v_pk_mul_f32 v[162:163], v[162:163], v[176:177] op_sel_hi:[1,0]
	s_mul_i32 s14, s13, 0xc000
	v_add_u32_e32 v198, s14, v194
	ds_write_b128 v198, v[148:151] offset:0
	ds_write_b128 v198, v[152:155] offset:128
	ds_write_b128 v198, v[116:119] offset:256
	ds_write_b128 v198, v[120:123] offset:384
	ds_write_b128 v198, v[140:143] offset:512
	ds_write_b128 v198, v[144:147] offset:640
	ds_write_b128 v198, v[164:167] offset:768
	ds_write_b128 v198, v[168:171] offset:896
	ds_write_b128 v198, v[156:159] offset:1024
	ds_write_b128 v198, v[160:163] offset:1152
	ds_write_b128 v198, v[100:103] offset:1280
	ds_write_b128 v198, v[104:107] offset:1408
	s_lshl_b32 s14, s13, 7
	v_add_u32_e32 v199, s14, v196
	s_lshl_b32 s14, s13, 8
	v_add_u32_e32 v198, s14, v197
	ds_write_b32 v199, v173
	ds_write_b64 v198, v[174:175]
	s_sub_u32 s50, s12, 1
	s_cmp_lt_u32 s50, 16
	s_cbranch_scc0 .Lhs_noproc
	s_lshr_b32 s51, s50, 1
	s_and_b32 s52, s50, 1
	s_mul_i32 s53, s51, 0x600
	v_add_u32_e32 v198, s53, v238
	s_lshl_b32 s54, s52, 7
	s_add_i32 s53, s53, s54
	v_add_u32_e32 v199, s53, v239
	ds_read_b128 v[84:87], v198 offset:768
	ds_read_b128 v[88:91], v198 offset:896
	ds_read_b128 v[92:95], v198 offset:256
	ds_read_b128 v[96:99], v198 offset:384
	ds_read_b128 v[100:103], v198 offset:1024
	ds_read_b128 v[104:107], v198 offset:1152
	ds_read_b128 v[108:111], v198 offset:512
	ds_read_b128 v[112:115], v198 offset:640
	ds_read_b128 v[116:119], v198
	ds_read_b128 v[120:123], v198 offset:128
	ds_read_b32 v124, v199
	s_lshl_b32 s53, s51, 8
	s_add_i32 s53, s53, s54
	v_add_u32_e32 v205, s53, v240
	s_waitcnt lgkmcnt(0)
	v_pk_mul_f32 v[128:129], v[242:243], v[84:85]
	v_pk_fma_f32 v[128:129], v[244:245], v[86:87], v[128:129]
	v_pk_fma_f32 v[128:129], v[246:247], v[88:89], v[128:129]
	v_pk_fma_f32 v[128:129], v[248:249], v[90:91], v[128:129]
	v_add_f32_e32 v126, v128, v129
	v_pk_mul_f32 v[242:243], v[242:243], v[92:93]
	v_pk_mul_f32 v[244:245], v[244:245], v[94:95]
	v_pk_mul_f32 v[246:247], v[246:247], v[96:97]
	v_pk_mul_f32 v[248:249], v[248:249], v[98:99]
	v_add_f32_dpp v126, v126, v126 quad_perm:[1,0,3,2] row_mask:0xf bank_mask:0xf bound_ctrl:1
	s_nop 0
	s_nop 0
	v_add_f32_dpp v126, v126, v126 quad_perm:[2,3,0,1] row_mask:0xf bank_mask:0xf bound_ctrl:1
	s_nop 0
	s_nop 0
	v_add_f32_dpp v126, v126, v126 row_half_mirror row_mask:0xf bank_mask:0xf bound_ctrl:1
	v_pk_fma_f32 v[242:243], v[100:101], v[126:127], v[242:243] op_sel_hi:[1,0,1]
	v_pk_fma_f32 v[244:245], v[102:103], v[126:127], v[244:245] op_sel_hi:[1,0,1]
	v_pk_fma_f32 v[246:247], v[104:105], v[126:127], v[246:247] op_sel_hi:[1,0,1]
	v_pk_fma_f32 v[248:249], v[106:107], v[126:127], v[248:249] op_sel_hi:[1,0,1]
	v_pk_fma_f32 v[242:243], v[108:109], v[124:125], v[242:243] op_sel_hi:[1,0,1]
	v_pk_fma_f32 v[244:245], v[110:111], v[124:125], v[244:245] op_sel_hi:[1,0,1]
	v_pk_fma_f32 v[246:247], v[112:113], v[124:125], v[246:247] op_sel_hi:[1,0,1]
	v_pk_fma_f32 v[248:249], v[114:115], v[124:125], v[248:249] op_sel_hi:[1,0,1]
	v_pk_mul_f32 v[128:129], v[242:243], v[116:117]
	v_pk_fma_f32 v[128:129], v[244:245], v[118:119], v[128:129]
	v_pk_fma_f32 v[128:129], v[246:247], v[120:121], v[128:129]
	v_pk_fma_f32 v[128:129], v[248:249], v[122:123], v[128:129]
	v_add_f32_e32 v130, v128, v129
	global_store_dwordx4 v[236:237], v[242:245], off
	global_store_dwordx4 v[236:237], v[246:249], off offset:128
	v_add_f32_dpp v130, v130, v130 quad_perm:[1,0,3,2] row_mask:0xf bank_mask:0xf bound_ctrl:1
	s_nop 0
	s_nop 0
	v_add_f32_dpp v130, v130, v130 quad_perm:[2,3,0,1] row_mask:0xf bank_mask:0xf bound_ctrl:1
	s_nop 0
	s_nop 0
	v_add_f32_dpp v130, v130, v130 row_half_mirror row_mask:0xf bank_mask:0xf bound_ctrl:1
	s_mov_b64 s[52:53], 0x2000
	v_lshl_add_u64 v[236:237], v[236:237], 0, s[52:53]
	ds_write_b32 v205, v130
.Lhs_noproc:
	s_cmp_lt_u32 s12, 16
	s_cbranch_scc0 .Lhs_noload
	global_load_dwordx4 v[242:245], v[250:251], off
	global_load_dwordx4 v[246:249], v[250:251], off offset:128
	s_mov_b64 s[52:53], 0x2000
	v_lshl_add_u64 v[250:251], v[250:251], 0, s[52:53]
.Lhs_noload:
	s_cmp_eq_u32 s12, 17
	s_cbranch_scc0 .Lhs_nofin
	s_cmp_lt_u32 s11, 6
	s_cbranch_scc0 .Lhs_nofin
	v_add_u32_e32 v84, 0xffffff00, v241
	v_lshrrev_b32_e32 v85, 4, v84
	v_and_b32_e32 v86, 15, v84
	v_lshlrev_b32_e32 v87, 8, v85
	v_lshl_add_u32 v87, v86, 4, v87
	v_add_u32_e32 v87, 0x1a400, v87
	v_lshlrev_b32_e32 v88, 2, v85
	v_add_u32_e32 v88, 0x1ac00, v88
	ds_read_b128 v[92:95], v87
	ds_read_b32 v96, v88
	s_lshl_b32 s50, s10, 3
	v_add_u32_e32 v89, s50, v85
	v_lshlrev_b32_e32 v90, 6, v89
	v_lshl_add_u32 v90, v86, 2, v90
	v_lshlrev_b32_e32 v90, 1, v90
	v_lshlrev_b32_e32 v91, 2, v89
	s_lshr_b32 s51, s8, 1
	s_add_i32 s51, s51, 0x4080
	s_lshl_b32 s52, s51, 11
	s_add_u32 s54, s86, 0x5700000
	s_addc_u32 s55, s87, 0
	s_add_u32 s54, s54, s52
	s_addc_u32 s55, s55, 0
	s_lshl_b32 s52, s51, 6
	s_add_u32 s56, s86, 0x7884000
	s_addc_u32 s57, s87, 0
	s_add_u32 s56, s56, s52
	s_addc_u32 s57, s57, 0
	v_cmp_eq_u32_e32 vcc, 0, v86
	s_waitcnt lgkmcnt(0)
	v_cvt_pk_bf16_f32 v92, v92, v93
	v_cvt_pk_bf16_f32 v93, v94, v95
	global_store_dwordx2 v90, v[92:93], s[54:55]
	s_and_saveexec_b64 s[58:59], vcc
	global_store_dword v91, v96, s[56:57]
	s_mov_b64 exec, s[58:59]
.Lhs_nofin:
	s_cmp_lt_u32 s12, 63
	s_cbranch_scc0 .Lh_nobuild
	s_mov_b64 s[0:1], 0x34000
	v_lshl_add_u64 v[178:179], v[178:179], 0, s[0:1]
	v_lshl_add_u64 v[180:181], v[180:181], 0, s[0:1]
	v_lshl_add_u64 v[182:183], v[182:183], 0, s[0:1]
	s_mov_b64 s[0:1], 0x10000
	v_lshl_add_u64 v[186:187], v[186:187], 0, s[0:1]
	v_lshl_add_u64 v[188:189], v[188:189], 0, s[0:1]
	global_load_dwordx2 v[52:53], v[178:179], off
	global_load_dwordx2 v[54:55], v[178:179], off offset:64
	global_load_dwordx2 v[56:57], v[178:179], off offset:2048
	global_load_dwordx2 v[58:59], v[178:179], off offset:2112
	global_load_dwordx2 v[60:61], v[180:181], off
	global_load_dwordx2 v[62:63], v[180:181], off offset:64
	global_load_dwordx2 v[64:65], v[182:183], off offset:-2560
	global_load_dwordx2 v[66:67], v[182:183], off offset:-2496
	global_load_dwordx2 v[68:69], v[182:183], off offset:-512
	global_load_dwordx2 v[70:71], v[182:183], off offset:-448
	global_load_dwordx2 v[72:73], v[178:179], off offset:-2560
	global_load_dwordx2 v[74:75], v[178:179], off offset:-2496
	global_load_dwordx2 v[76:77], v[186:187], off
	global_load_dwordx2 v[78:79], v[186:187], off offset:64
	global_load_dwordx2 v[80:81], v[188:189], off
	global_load_dwordx2 v[82:83], v[188:189], off offset:64
